# as previous with the first V-fragment LDS reads issued inside the QK MFMA block instead of right after the step barrier
# speedup vs baseline: 1.0254x; 1.0069x over previous
; __device__ __forceinline__ void finishSM(f32x16& p0, f32x16& p1, float alpha, float& l_reg, bf16x8& pa0, bf16x8& pa1, bf16x8& pa2, bf16x8& pa3) {
;   for (int r = 0; r < 16; ++r) p1[r] = __builtin_amdgcn_exp2f(p1[r]);
;   float ps = 0; for (int r = 0; r < 16; ++r) ps += p0[r]; for (int r = 0; r < 16; ++r) ps += p1[r];
;   { auto rr = __builtin_amdgcn_permlane32_swap(__float_as_uint(ps), __float_as_uint(ps), false, false);
;     ps = __uint_as_float(rr[0]) + __uint_as_float(rr[1]); }
;   l_reg = l_reg * alpha + ps;
;     ...
;   PK4(p0, 0, pa0); PK4(p0, 8, pa1); PK4(p1, 0, pa2); PK4(p1, 8, pa3);
;     ...
; }
; __device__ __forceinline__ void kload(bf16x8 (&kf)[8], const char* Ks, int r32, int hi, int sb) {
; #pragma unroll
;   for (int d0 = 0; d0 < 4; ++d0) { const int cb = sb + (d0 * 16 + hi * 8) * 2;
;     kf[2 * d0] = *reinterpret_cast<const bf16x8*>(Ks + KSWZ(r32, cb)); kf[2 * d0 + 1] = *reinterpret_cast<const bf16x8*>(Ks + KSWZ(32 + r32, cb)); }
; }
; __device__ __forceinline__ void kmma(f32x16& p0, f32x16& p1, const bf16x8 (&kf)[8], const bf16x8* qr) {
;   asm volatile("s_waitcnt lgkmcnt(0)" ::: "memory"); SBAR();
;   p0 = f32x16{}; p1 = f32x16{};
; #pragma unroll
;   for (int d0 = 0; d0 < 4; ++d0) { p0 = __builtin_amdgcn_mfma_f32_32x32x16_bf16(kf[2 * d0], qr[d0], p0, 0, 0, 0); p1 = __builtin_amdgcn_mfma_f32_32x32x16_bf16(kf[2 * d0 + 1], qr[d0], p1, 0, 0, 0); }
; }
; __device__ __forceinline__ void qkt(f32x16& p0, f32x16& p1, const char* Ks, const bf16x8* qr, int r32, int hi, int sb) {
;   bf16x8 kf[8]; kload(kf, Ks, r32, hi, sb); SBAR(); kmma(p0, p1, kf, qr);
; }
; __device__ __forceinline__ int v_st(int k, int c) { const int kk = (k & ~0xC) | ((k & 4) << 1) | ((k & 8) >> 1); return ((kk >> 3) * 4 + (c >> 5)) * 512 + ((kk & 7) * 32 + (c & 31)) * 2; }
; __device__ __forceinline__ int v_rd_base(int lane) { return ((lane & 3) << 3) | (((lane >> 2) & 3) << 6) | (((lane >> 4) & 1) << 5) | (((lane >> 5) & 1) << 8); }
; template <int OFF> __device__ __forceinline__ s16x4 tr_read(int vb) {
;   s16x4 r; asm volatile("ds_read_b64_tr_b16 %0, %1 offset:%2" : "=&v"(r) : "v"(vb), "i"(OFF) : "memory"); return r;
; }
; template <int D0> __device__ __forceinline__ void v_frag_read(VFrag& f, int vb) {
;   f.l0 = tr_read<v_rd_off(D0, 0, 0)>(vb); f.h0 = tr_read<v_rd_off(D0, 0, 1)>(vb); f.l1 = tr_read<v_rd_off(D0, 1, 0)>(vb); f.h1 = tr_read<v_rd_off(D0, 1, 1)>(vb);
.LBB0_770:
	ds_read_b128 v[82:85], v245
	ds_read_b128 v[86:89], v245 offset:8192
	ds_read_b128 v[130:133], v246
	ds_read_b128 v[134:137], v246 offset:8192
	ds_read_b128 v[206:209], v247
	ds_read_b128 v[210:213], v247 offset:8192
	ds_read_b128 v[214:217], v255
	ds_read_b128 v[218:221], v255 offset:8192
	v_exp_f32_e32 v148, v66
	v_add_f32_e32 v66, 0, v175
	v_add_f32_e32 v66, v177, v66
	v_add_f32_e32 v66, v192, v66
	v_add_f32_e32 v66, v195, v66
	v_add_f32_e32 v66, v196, v66
	v_add_f32_e32 v66, v199, v66
	v_add_f32_e32 v66, v200, v66
	v_add_f32_e32 v66, v203, v66
	v_add_f32_e32 v66, v176, v66
	v_add_f32_e32 v66, v193, v66
	v_add_f32_e32 v66, v194, v66
	v_add_f32_e32 v66, v197, v66
	v_add_f32_e32 v66, v198, v66
	v_exp_f32_e32 v149, v67
	v_add_f32_e32 v66, v201, v66
	s_waitcnt lgkmcnt(7)
	v_mfma_f32_32x32x16_bf16 v[98:113], v[82:85], v[126:129], 0
	v_exp_f32_e32 v150, v68
	s_and_b32 s13, s36, 0xc000
	v_add_f32_e32 v66, v202, v66
	v_add_u32_e32 v244, s13, v164
	v_exp_f32_e32 v151, v69
	ds_read_b64_tr_b16 v[228:229], v244 offset:0
	v_add_f32_e32 v66, v204, v66
	ds_read_b64_tr_b16 v[230:231], v244 offset:0x800
	ds_read_b64_tr_b16 v[232:233], v244 offset:0x1000
	ds_read_b64_tr_b16 v[234:235], v244 offset:0x1800
	s_waitcnt lgkmcnt(10)
	v_mfma_f32_32x32x16_bf16 v[82:97], v[86:89], v[126:129], 0
	v_exp_f32_e32 v186, v70
	ds_read_b64_tr_b16 v[236:237], v244 offset:0x2000
	v_add_f32_e32 v66, v148, v66
	ds_read_b64_tr_b16 v[238:239], v244 offset:0x2800
	v_exp_f32_e32 v187, v71
	ds_read_b64_tr_b16 v[240:241], v244 offset:0x3000
	v_add_f32_e32 v66, v149, v66
	ds_read_b64_tr_b16 v[242:243], v244 offset:0x3800
	v_exp_f32_e32 v188, v72
	s_add_i32 s37, s12, 2
	s_cmpk_lt_u32 s12, 0x7e
	s_cselect_b64 s[0:1], -1, 0
	s_waitcnt lgkmcnt(13)
	v_mfma_f32_32x32x16_bf16 v[98:113], v[130:133], v[122:125], v[98:113]
	v_add_f32_e32 v66, v150, v66
	s_and_b64 s[10:11], s[0:1], exec
	v_exp_f32_e32 v189, v73
	s_cselect_b32 s10, 0, 0xffffff80
	v_add_f32_e32 v66, v151, v66
	s_add_i32 s58, s37, s10
	v_exp_f32_e32 v205, v74
	s_and_b64 s[0:1], s[0:1], exec
	s_cselect_b32 s1, s9, s30
	s_cselect_b32 s0, s8, s26
	s_lshl_b64 s[10:11], s[58:59], 17
	s_waitcnt lgkmcnt(12)
	v_mfma_f32_32x32x16_bf16 v[82:97], v[134:137], v[122:125], v[82:97]
	v_add_f32_e32 v66, v186, v66
	s_lshl_b64 s[0:1], s[0:1], 11
	v_exp_f32_e32 v222, v75
	s_add_u32 s10, s10, s0
	v_add_f32_e32 v66, v187, v66
	s_addc_u32 s11, s11, s1
	v_exp_f32_e32 v223, v76
	s_add_u32 s0, s20, s10
	v_add_f32_e32 v66, v188, v66
	s_addc_u32 s1, s21, s11
	s_add_u32 s10, s22, s10
	s_addc_u32 s11, s23, s11
	s_waitcnt lgkmcnt(11)
	v_mfma_f32_32x32x16_bf16 v[98:113], v[206:209], v[118:121], v[98:113]
	v_exp_f32_e32 v224, v77
	s_and_b32 s13, s37, 0xff
	v_add_f32_e32 v66, v189, v66
	s_mulk_i32 s13, 0xab
	v_exp_f32_e32 v225, v78
	s_lshr_b32 s13, s13, 9
	v_add_f32_e32 v66, v205, v66
	s_mul_i32 s13, s13, 3
	s_sub_i32 s13, s37, s13
	s_and_b32 s13, s13, 0xff
	s_waitcnt lgkmcnt(10)
	v_mfma_f32_32x32x16_bf16 v[82:97], v[210:213], v[118:121], v[82:97]
	v_exp_f32_e32 v226, v79
	s_lshl_b32 s13, s13, 14
	s_mov_b32 s100, s13
	v_add_f32_e32 v66, v222, v66
	s_add_i32 s42, s36, 0xffffc000
	v_exp_f32_e32 v227, v80
	s_and_b32 s42, s42, 0xc000
	v_add_f32_e32 v66, v223, v66
	s_add_i32 s13, s13, s27
	v_exp_f32_e32 v81, v81
	s_add_i32 s42, s42, s31
	v_lshl_add_u64 v[246:247], s[0:1], 0, v[146:147]
	s_mov_b32 m0, s13
	s_waitcnt lgkmcnt(9)
	v_mfma_f32_32x32x16_bf16 v[98:113], v[214:217], v[114:117], v[98:113]
	v_add_f32_e32 v66, v224, v66
	s_nop 0
	v_add_f32_e32 v66, v225, v66
	global_load_lds_dwordx4 v[246:247], off
	v_add_f32_e32 v66, v226, v66
	v_lshl_add_u64 v[246:247], s[10:11], 0, v[142:143]
	v_add_f32_e32 v66, v227, v66
	s_mov_b32 m0, s42
	s_nop 0
	global_load_lds_dwordx4 v[246:247], off
	v_lshl_add_u64 v[246:247], s[0:1], 0, v[144:145]
	s_waitcnt lgkmcnt(8)
	v_mfma_f32_32x32x16_bf16 v[82:97], v[218:221], v[114:117], v[82:97]
	v_add_f32_e32 v130, v81, v66
	s_add_i32 m0, s13, 0x2000
	v_mov_b32_e32 v131, v130
	s_nop 0
	v_cvt_pk_bf16_f32 v66, v175, v177
	global_load_lds_dwordx4 v[246:247], off
	v_cvt_pk_bf16_f32 v67, v192, v195
	v_lshl_add_u64 v[246:247], s[10:11], 0, v[154:155]
	v_cvt_pk_bf16_f32 v68, v196, v199
	s_add_i32 m0, s42, 0x2000
	s_nop 0
	global_load_lds_dwordx4 v[246:247], off
	v_permlane32_swap_b32_e32 v130, v131
	v_cvt_pk_bf16_f32 v69, v200, v203
	v_permlane32_swap_b32_e32 v66, v68
	v_cvt_pk_bf16_f32 v70, v176, v193
	v_cvt_pk_bf16_f32 v71, v194, v197
	v_cvt_pk_bf16_f32 v72, v198, v201
	v_cvt_pk_bf16_f32 v73, v202, v204
	v_cvt_pk_bf16_f32 v74, v148, v149
	v_cvt_pk_bf16_f32 v75, v150, v151
	v_cvt_pk_bf16_f32 v76, v186, v187
	v_cvt_pk_bf16_f32 v77, v188, v189
	v_cvt_pk_bf16_f32 v78, v205, v222
	v_cvt_pk_bf16_f32 v79, v223, v224
	v_cvt_pk_bf16_f32 v80, v225, v226
	v_cvt_pk_bf16_f32 v81, v227, v81
	v_permlane32_swap_b32_e32 v67, v69
	v_permlane32_swap_b32_e32 v70, v72
	v_permlane32_swap_b32_e32 v71, v73
	v_permlane32_swap_b32_e32 v74, v76
	v_permlane32_swap_b32_e32 v75, v77
	v_permlane32_swap_b32_e32 v78, v80
	v_permlane32_swap_b32_e32 v79, v81
	ds_read_b64_tr_b16 v[204:205], v244 offset:0x200
	ds_read_b64_tr_b16 v[206:207], v244 offset:0xa00
	ds_read_b64_tr_b16 v[208:209], v244 offset:0x1200
	ds_read_b64_tr_b16 v[210:211], v244 offset:0x1a00
	ds_read_b64_tr_b16 v[212:213], v244 offset:0x2200
	ds_read_b64_tr_b16 v[214:215], v244 offset:0x2a00
	ds_read_b64_tr_b16 v[216:217], v244 offset:0x3200
	ds_read_b64_tr_b16 v[218:219], v244 offset:0x3a00
	s_waitcnt lgkmcnt(14)
	v_mfma_f32_32x32x16_bf16 v[18:33], v[66:69], v[228:231], v[18:33]
	v_max_f32_e32 v245, v99, v99
	v_max_f32_e32 v246, v98, v98
	v_max_f32_e32 v245, v246, v245
	v_max3_f32 v245, v245, v100, v101
	v_max3_f32 v245, v245, v102, v103
	v_max3_f32 v245, v245, v104, v105
	v_max3_f32 v245, v245, v106, v107
	v_max3_f32 v245, v245, v108, v109
	s_waitcnt lgkmcnt(12)
; #define SBAR() __builtin_amdgcn_sched_barrier(0)
; __device__ __forceinline__ void partialSM(f32x16& p0, f32x16& p1, float& m_reg, float& mn, float& alpha) {
;   constexpr float C = SCALE * 1.4426950408889634f;
;   float pmax = p0[0]; for (int r = 1; r < 16; ++r) pmax = fmaxf(pmax, p0[r]); for (int r = 0; r < 16; ++r) pmax = fmaxf(pmax, p1[r]);
;   { auto rr = __builtin_amdgcn_permlane32_swap(__float_as_uint(pmax), __float_as_uint(pmax), false, false);
;     pmax = fmaxf(__uint_as_float(rr[0]), __uint_as_float(rr[1])); }
;   if (__builtin_expect(__all(pmax - m_reg <= THR / SCALE), 1)) { mn = m_reg; alpha = 1.f; }
;   else { mn = fmaxf(m_reg, pmax); alpha = __builtin_amdgcn_exp2f((m_reg - mn) * C); m_reg = mn; }
;   float mnC = -mn * C;
;   for (int r = 0; r < 16; ++r) p0[r] = fmaf(p0[r], C, mnC); for (int r = 0; r < 16; ++r) p1[r] = fmaf(p1[r], C, mnC);
;   for (int r = 0; r < 16; ++r) p0[r] = __builtin_amdgcn_exp2f(p0[r]);
; }
; __device__ __forceinline__ void pv_d0(f32x16* o, int vb, bf16x8 pa0, bf16x8 pa1, bf16x8 pa2, bf16x8 pa3) {
;   VFrag fa, fb;
;   v_frag_read<0>(fa, vb);
;   asm volatile("s_waitcnt lgkmcnt(0)" ::: "memory"); SBAR();
;   v_frag_read<1>(fb, vb); SBAR();
;   pv_mma(o[0], fa, pa0, pa1, pa2, pa3); SBAR();
;   asm volatile("s_waitcnt lgkmcnt(0)" ::: "memory"); SBAR();
;   v_frag_read<2>(fa, vb); SBAR();
;   pv_mma(o[1], fb, pa0, pa1, pa2, pa3); SBAR();
;   asm volatile("s_waitcnt lgkmcnt(0)" ::: "memory"); SBAR();
;   v_frag_read<3>(fb, vb); SBAR();
;   pv_mma(o[2], fa, pa0, pa1, pa2, pa3); SBAR();
;   asm volatile("s_waitcnt lgkmcnt(0)" ::: "memory"); SBAR();
;   pv_mma(o[3], fb, pa0, pa1, pa2, pa3);
; }
	v_mfma_f32_32x32x16_bf16 v[18:33], v[70:73], v[232:235], v[18:33]
	v_max3_f32 v245, v245, v110, v111
	v_max3_f32 v245, v245, v112, v113
	v_max3_f32 v245, v245, v82, v83
	v_max3_f32 v245, v245, v84, v85
	v_max3_f32 v245, v245, v86, v87
	v_max3_f32 v245, v245, v88, v89
	v_max3_f32 v245, v245, v90, v91
	v_max3_f32 v245, v245, v92, v93
	s_waitcnt lgkmcnt(10)
	v_mfma_f32_32x32x16_bf16 v[18:33], v[74:77], v[236:239], v[18:33]
	v_max3_f32 v245, v245, v94, v95
	v_max3_f32 v245, v245, v96, v97
	v_mov_b32_e32 v246, v245
	s_nop 1
	v_permlane32_swap_b32_e32 v245, v246
	v_max_f32_e32 v246, v246, v246
	v_max_f32_e32 v245, v245, v245
	v_max_f32_e32 v245, v245, v246
	v_sub_f32_e32 v246, v245, v174
	s_waitcnt lgkmcnt(8)
	v_mfma_f32_32x32x16_bf16 v[18:33], v[78:81], v[240:243], v[18:33]
	v_cmp_ge_f32_e32 vcc, s63, v246
	v_max_f32_e32 v246, v174, v174
	v_max_f32_e32 v245, v246, v245
	v_sub_f32_e32 v246, v174, v245
	v_mul_f32_e32 v246, 0x3e38aa3b, v246
	v_exp_f32_e32 v246, v246
	s_cmp_eq_u64 vcc, exec
	s_cselect_b64 s[0:1], -1, 0
	v_cndmask_b32_e64 v132, v246, 1.0, s[0:1]
	ds_read_b64_tr_b16 v[228:229], v244 offset:0x400
	ds_read_b64_tr_b16 v[230:231], v244 offset:0xc00
	ds_read_b64_tr_b16 v[232:233], v244 offset:0x1400
	ds_read_b64_tr_b16 v[234:235], v244 offset:0x1c00
	ds_read_b64_tr_b16 v[236:237], v244 offset:0x2400
	ds_read_b64_tr_b16 v[238:239], v244 offset:0x2c00
	ds_read_b64_tr_b16 v[240:241], v244 offset:0x3400
	ds_read_b64_tr_b16 v[242:243], v244 offset:0x3c00
	v_cndmask_b32_e64 v133, v245, v174, s[0:1]
	v_mul_f32_e32 v148, 0xbe38aa3b, v133
	s_waitcnt lgkmcnt(14)
	v_mfma_f32_32x32x16_bf16 v[50:65], v[66:69], v[204:207], v[50:65]
	v_fmamk_f32 v98, v98, 0x3e38aa3b, v148
	v_fmamk_f32 v99, v99, 0x3e38aa3b, v148
	v_fmamk_f32 v100, v100, 0x3e38aa3b, v148
	v_fmamk_f32 v101, v101, 0x3e38aa3b, v148
	s_waitcnt lgkmcnt(12)
	v_mfma_f32_32x32x16_bf16 v[50:65], v[70:73], v[208:211], v[50:65]
	v_fmamk_f32 v102, v102, 0x3e38aa3b, v148
	v_fmamk_f32 v103, v103, 0x3e38aa3b, v148
	v_fmamk_f32 v104, v104, 0x3e38aa3b, v148
	v_fmamk_f32 v105, v105, 0x3e38aa3b, v148
	s_waitcnt lgkmcnt(10)
	v_mfma_f32_32x32x16_bf16 v[50:65], v[74:77], v[212:215], v[50:65]
	v_fmamk_f32 v106, v106, 0x3e38aa3b, v148
	v_fmamk_f32 v107, v107, 0x3e38aa3b, v148
	v_fmamk_f32 v108, v108, 0x3e38aa3b, v148
	v_fmamk_f32 v109, v109, 0x3e38aa3b, v148
	s_waitcnt lgkmcnt(8)
	v_mfma_f32_32x32x16_bf16 v[50:65], v[78:81], v[216:219], v[50:65]
	v_fmamk_f32 v110, v110, 0x3e38aa3b, v148
	v_fmamk_f32 v111, v111, 0x3e38aa3b, v148
	v_fmamk_f32 v112, v112, 0x3e38aa3b, v148
	v_fmamk_f32 v113, v113, 0x3e38aa3b, v148
	ds_read_b64_tr_b16 v[204:205], v244 offset:0x600
	ds_read_b64_tr_b16 v[206:207], v244 offset:0xe00
	ds_read_b64_tr_b16 v[208:209], v244 offset:0x1600
	ds_read_b64_tr_b16 v[210:211], v244 offset:0x1e00
	ds_read_b64_tr_b16 v[212:213], v244 offset:0x2600
	ds_read_b64_tr_b16 v[214:215], v244 offset:0x2e00
	ds_read_b64_tr_b16 v[216:217], v244 offset:0x3600
	ds_read_b64_tr_b16 v[218:219], v244 offset:0x3e00
	s_waitcnt lgkmcnt(14)
	v_mfma_f32_32x32x16_bf16 v[34:49], v[66:69], v[228:231], v[34:49]
	v_fmamk_f32 v82, v82, 0x3e38aa3b, v148
	v_fmamk_f32 v83, v83, 0x3e38aa3b, v148
	v_fmamk_f32 v84, v84, 0x3e38aa3b, v148
	v_fmamk_f32 v85, v85, 0x3e38aa3b, v148
	s_waitcnt lgkmcnt(12)
	v_mfma_f32_32x32x16_bf16 v[34:49], v[70:73], v[232:235], v[34:49]
	v_fmamk_f32 v86, v86, 0x3e38aa3b, v148
	v_fmamk_f32 v87, v87, 0x3e38aa3b, v148
	s_add_i32 s13, s36, 0xffff4000
	v_fmamk_f32 v149, v88, 0x3e38aa3b, v148
	s_waitcnt lgkmcnt(10)
	v_mfma_f32_32x32x16_bf16 v[34:49], v[74:77], v[236:239], v[34:49]
	v_fmamk_f32 v150, v89, 0x3e38aa3b, v148
	v_fmamk_f32 v151, v90, 0x3e38aa3b, v148
	v_fmamk_f32 v186, v91, 0x3e38aa3b, v148
	v_fmamk_f32 v187, v92, 0x3e38aa3b, v148
	s_waitcnt lgkmcnt(8)
	v_mfma_f32_32x32x16_bf16 v[34:49], v[78:81], v[240:243], v[34:49]
	v_fmamk_f32 v188, v93, 0x3e38aa3b, v148
	v_fmamk_f32 v189, v94, 0x3e38aa3b, v148
	v_exp_f32_e32 v192, v98
	v_exp_f32_e32 v193, v99
	v_exp_f32_e32 v194, v100
	v_exp_f32_e32 v195, v101
	s_waitcnt lgkmcnt(6)
	v_mfma_f32_32x32x16_bf16 v[2:17], v[66:69], v[204:207], v[2:17]
	v_exp_f32_e32 v196, v102
	v_exp_f32_e32 v197, v103
	v_exp_f32_e32 v198, v104
	v_exp_f32_e32 v199, v105
	s_waitcnt lgkmcnt(4)
	v_mfma_f32_32x32x16_bf16 v[2:17], v[70:73], v[208:211], v[2:17]
	v_exp_f32_e32 v200, v106
	v_exp_f32_e32 v201, v107
	v_exp_f32_e32 v202, v108
	v_exp_f32_e32 v203, v109
	v_exp_f32_e32 v204, v110
	v_exp_f32_e32 v205, v111
	s_waitcnt lgkmcnt(2)
	v_mfma_f32_32x32x16_bf16 v[2:17], v[74:77], v[212:215], v[2:17]
	v_exp_f32_e32 v206, v112
	v_exp_f32_e32 v207, v113
	v_fmamk_f32 v208, v95, 0x3e38aa3b, v148
	v_fmamk_f32 v209, v96, 0x3e38aa3b, v148
	v_fmac_f32_e32 v148, 0x3e38aa3b, v97
	s_waitcnt lgkmcnt(0)
	v_mfma_f32_32x32x16_bf16 v[2:17], v[78:81], v[216:219], v[2:17]
	v_add_u32_e32 v245, s101, v169
	v_add_u32_e32 v246, s101, v170
	v_add_u32_e32 v247, s101, v171
	v_add_u32_e32 v255, s101, v172
	v_cmp_gt_f32_e32 vcc, 1.0, v132
	s_cbranch_vccz .LBB0_774
	s_and_saveexec_b64 s[10:11], s[40:41]
	ds_write_b32 v162, v132 offset:128
	s_or_b64 exec, exec, s[10:11]
	s_waitcnt lgkmcnt(0)
	v_add_u32_e32 v67, s18, v140
	ds_read_b128 v[68:71], v67 offset:224
	ds_read_b128 v[72:75], v67 offset:192
	ds_read_b128 v[76:79], v67 offset:160
	ds_read_b128 v[134:137], v67 offset:128
	s_waitcnt lgkmcnt(0)
	v_pk_mul_f32 v[30:31], v[30:31], v[68:69]
	v_pk_mul_f32 v[26:27], v[26:27], v[72:73]
	v_pk_mul_f32 v[22:23], v[22:23], v[76:77]
	v_pk_mul_f32 v[32:33], v[32:33], v[70:71]
	v_pk_mul_f32 v[28:29], v[28:29], v[74:75]
	v_pk_mul_f32 v[24:25], v[24:25], v[78:79]
	v_pk_mul_f32 v[20:21], v[20:21], v[136:137]
	v_pk_mul_f32 v[18:19], v[18:19], v[134:135]
	v_pk_mul_f32 v[62:63], v[62:63], v[68:69]
	v_pk_mul_f32 v[58:59], v[58:59], v[72:73]
	v_pk_mul_f32 v[54:55], v[54:55], v[76:77]
	v_pk_mul_f32 v[64:65], v[64:65], v[70:71]
	v_pk_mul_f32 v[60:61], v[60:61], v[74:75]
	v_pk_mul_f32 v[56:57], v[56:57], v[78:79]
	v_pk_mul_f32 v[52:53], v[52:53], v[136:137]
	v_pk_mul_f32 v[50:51], v[50:51], v[134:135]
	v_pk_mul_f32 v[46:47], v[46:47], v[68:69]
	v_pk_mul_f32 v[42:43], v[42:43], v[72:73]
	v_pk_mul_f32 v[38:39], v[38:39], v[76:77]
	v_pk_mul_f32 v[48:49], v[48:49], v[70:71]
	v_pk_mul_f32 v[44:45], v[44:45], v[74:75]
	v_pk_mul_f32 v[40:41], v[40:41], v[78:79]
	v_pk_mul_f32 v[36:37], v[36:37], v[136:137]
	v_pk_mul_f32 v[34:35], v[34:35], v[134:135]
	v_pk_mul_f32 v[14:15], v[14:15], v[68:69]
	v_pk_mul_f32 v[10:11], v[10:11], v[72:73]
	v_pk_mul_f32 v[6:7], v[6:7], v[76:77]
	v_pk_mul_f32 v[16:17], v[16:17], v[70:71]
	v_pk_mul_f32 v[12:13], v[12:13], v[74:75]
	v_pk_mul_f32 v[8:9], v[8:9], v[78:79]
	v_pk_mul_f32 v[4:5], v[4:5], v[136:137]
	v_pk_mul_f32 v[2:3], v[2:3], v[134:135]
; #define SBAR() __builtin_amdgcn_sched_barrier(0)
; __device__ __forceinline__ void finishSM(f32x16& p0, f32x16& p1, float alpha, float& l_reg, bf16x8& pa0, bf16x8& pa1, bf16x8& pa2, bf16x8& pa3) {
;   for (int r = 0; r < 16; ++r) p1[r] = __builtin_amdgcn_exp2f(p1[r]);
;   float ps = 0; for (int r = 0; r < 16; ++r) ps += p0[r]; for (int r = 0; r < 16; ++r) ps += p1[r];
;   { auto rr = __builtin_amdgcn_permlane32_swap(__float_as_uint(ps), __float_as_uint(ps), false, false);
;     ps = __uint_as_float(rr[0]) + __uint_as_float(rr[1]); }
;   l_reg = l_reg * alpha + ps;
;     ...
;   PK4(p0, 0, pa0); PK4(p0, 8, pa1); PK4(p1, 0, pa2); PK4(p1, 8, pa3);
;     ...
; }
; __device__ __forceinline__ void kload(bf16x8 (&kf)[8], const char* Ks, int r32, int hi, int sb) {
; #pragma unroll
;   for (int d0 = 0; d0 < 4; ++d0) { const int cb = sb + (d0 * 16 + hi * 8) * 2;
;     kf[2 * d0] = *reinterpret_cast<const bf16x8*>(Ks + KSWZ(r32, cb)); kf[2 * d0 + 1] = *reinterpret_cast<const bf16x8*>(Ks + KSWZ(32 + r32, cb)); }
; }
; __device__ __forceinline__ void kmma(f32x16& p0, f32x16& p1, const bf16x8 (&kf)[8], const bf16x8* qr) {
;   asm volatile("s_waitcnt lgkmcnt(0)" ::: "memory"); SBAR();
;   p0 = f32x16{}; p1 = f32x16{};
; #pragma unroll
;   for (int d0 = 0; d0 < 4; ++d0) { p0 = __builtin_amdgcn_mfma_f32_32x32x16_bf16(kf[2 * d0], qr[d0], p0, 0, 0, 0); p1 = __builtin_amdgcn_mfma_f32_32x32x16_bf16(kf[2 * d0 + 1], qr[d0], p1, 0, 0, 0); }
; }
; __device__ __forceinline__ void qkt(f32x16& p0, f32x16& p1, const char* Ks, const bf16x8* qr, int r32, int hi, int sb) {
;   bf16x8 kf[8]; kload(kf, Ks, r32, hi, sb); SBAR(); kmma(p0, p1, kf, qr);
.LBB0_774:
	s_waitcnt vmcnt(4)
	s_barrier
	ds_read_b128 v[66:69], v245
	ds_read_b128 v[70:73], v245 offset:8192
	ds_read_b128 v[98:101], v246
	ds_read_b128 v[102:105], v246 offset:8192
	ds_read_b128 v[106:109], v247
	ds_read_b128 v[110:113], v247 offset:8192
	ds_read_b128 v[134:137], v255
	ds_read_b128 v[174:177], v255 offset:8192
	v_exp_f32_e32 v210, v82
	v_exp_f32_e32 v211, v83
	v_exp_f32_e32 v212, v84
	v_exp_f32_e32 v213, v85
	v_exp_f32_e32 v214, v86
	v_exp_f32_e32 v215, v87
	v_add_f32_e32 v216, 0, v192
	v_add_f32_e32 v216, v193, v216
	v_add_f32_e32 v216, v194, v216
	v_add_f32_e32 v216, v195, v216
	v_exp_f32_e32 v149, v149
	v_exp_f32_e32 v150, v150
	v_exp_f32_e32 v151, v151
	v_exp_f32_e32 v186, v186
	v_exp_f32_e32 v187, v187
	v_exp_f32_e32 v188, v188
	s_waitcnt lgkmcnt(7)
	v_mfma_f32_32x32x16_bf16 v[82:97], v[66:69], v[126:129], 0
	v_exp_f32_e32 v189, v189
	s_and_b32 s46, s13, 0xc000
	v_exp_f32_e32 v208, v208
	v_add_u32_e32 v244, s46, v164
	v_exp_f32_e32 v209, v209
	ds_read_b64_tr_b16 v[228:229], v244 offset:0
	v_exp_f32_e32 v148, v148
	ds_read_b64_tr_b16 v[230:231], v244 offset:0x800
	ds_read_b64_tr_b16 v[232:233], v244 offset:0x1000
	s_waitcnt lgkmcnt(9)
	v_mfma_f32_32x32x16_bf16 v[66:81], v[70:73], v[126:129], 0
	v_add_f32_e32 v255, v196, v216
	ds_read_b64_tr_b16 v[234:235], v244 offset:0x1800
	v_add_f32_e32 v255, v197, v255
	ds_read_b64_tr_b16 v[236:237], v244 offset:0x2000
	v_add_f32_e32 v255, v198, v255
	ds_read_b64_tr_b16 v[238:239], v244 offset:0x2800
	v_add_f32_e32 v255, v199, v255
	ds_read_b64_tr_b16 v[240:241], v244 offset:0x3000
	v_add_f32_e32 v255, v200, v255
	ds_read_b64_tr_b16 v[242:243], v244 offset:0x3800
	s_waitcnt lgkmcnt(13)
	v_mfma_f32_32x32x16_bf16 v[82:97], v[98:101], v[122:125], v[82:97]
	v_add_f32_e32 v255, v201, v255
	s_add_i32 s46, s12, 3
	v_add_f32_e32 v255, v202, v255
	s_cmpk_lt_u32 s12, 0x7d
	v_add_f32_e32 v255, v203, v255
	s_cselect_b64 s[42:43], -1, 0
	v_add_f32_e32 v255, v204, v255
	s_and_b64 s[44:45], s[42:43], exec
	s_cselect_b32 s44, 0, 0xffffff80
	s_waitcnt lgkmcnt(12)
	v_mfma_f32_32x32x16_bf16 v[66:81], v[102:105], v[122:125], v[66:81]
	v_add_f32_e32 v255, v205, v255
	s_add_i32 s58, s46, s44
	v_add_f32_e32 v255, v206, v255
	s_and_b64 s[42:43], s[42:43], exec
	v_add_f32_e32 v255, v207, v255
	s_cselect_b32 s43, s9, s30
	v_add_f32_e32 v255, v210, v255
	s_cselect_b32 s42, s8, s26
	v_add_f32_e32 v255, v211, v255
	s_lshl_b64 s[44:45], s[58:59], 17
	s_waitcnt lgkmcnt(11)
	v_mfma_f32_32x32x16_bf16 v[82:97], v[106:109], v[118:121], v[82:97]
	v_add_f32_e32 v255, v212, v255
	s_lshl_b64 s[42:43], s[42:43], 11
	v_add_f32_e32 v255, v213, v255
	s_add_u32 s44, s44, s42
	v_add_f32_e32 v255, v214, v255
	s_addc_u32 s45, s45, s43
	v_add_f32_e32 v255, v215, v255
	s_add_u32 s42, s20, s44
	s_addc_u32 s43, s21, s45
	s_waitcnt lgkmcnt(10)
	v_mfma_f32_32x32x16_bf16 v[66:81], v[110:113], v[118:121], v[66:81]
	v_add_f32_e32 v255, v149, v255
	s_add_u32 s44, s22, s44
	v_add_f32_e32 v255, v150, v255
	s_mul_i32 s47, s46, 0xab
	v_add_f32_e32 v255, v151, v255
	s_addc_u32 s45, s23, s45
	v_add_f32_e32 v255, v186, v255
	s_bfe_u32 s47, s47, 0x70009
	v_add_f32_e32 v255, v187, v255
	s_mul_i32 s47, s47, 3
	s_waitcnt lgkmcnt(9)
	v_mfma_f32_32x32x16_bf16 v[82:97], v[134:137], v[114:117], v[82:97]
	v_add_f32_e32 v255, v188, v255
	s_sub_i32 s46, s46, s47
	v_add_f32_e32 v255, v189, v255
	s_and_b32 s46, s46, 0xff
	v_add_f32_e32 v255, v208, v255
	s_lshl_b32 s46, s46, 14
	s_mov_b32 s101, s46
	v_add_f32_e32 v255, v209, v255
	s_add_i32 s46, s46, s27
	v_add_f32_e32 v99, v148, v255
	s_and_b32 s47, s36, 0xc000
	s_add_i32 s47, s47, s31
	s_cmpk_gt_u32 s12, 0x80
	s_cselect_b64 s[10:11], -1, 0
	s_and_b64 vcc, exec, s[10:11]
	s_cbranch_vccnz .LBB0_776
	v_lshl_add_u64 v[246:247], s[42:43], 0, v[146:147]
	s_mov_b32 m0, s46
	s_nop 0
	global_load_lds_dwordx4 v[246:247], off
	v_lshl_add_u64 v[246:247], s[44:45], 0, v[142:143]
	s_mov_b32 m0, s47
	s_nop 0
	global_load_lds_dwordx4 v[246:247], off
	v_lshl_add_u64 v[246:247], s[42:43], 0, v[144:145]
	s_add_i32 m0, s46, 0x2000
	s_nop 0
	global_load_lds_dwordx4 v[246:247], off
	v_lshl_add_u64 v[246:247], s[44:45], 0, v[154:155]
	s_add_i32 m0, s47, 0x2000
	s_nop 0
	global_load_lds_dwordx4 v[246:247], off
